# phase 14 LN2: the next iteration's four rows are fetched into free registers while the current rows are normalised and stored; loop top waits vmcnt(16) (stores may still fly)
# speedup vs baseline: 1.0036x; 1.0036x over previous
.LBB0_1616:
	s_cmp_lt_i32 s68, 15
	s_cselect_b64 s[6:7], -1, 0
	s_and_b64 s[4:5], s[6:7], s[4:5]
	s_andn2_b64 vcc, exec, s[4:5]
	s_cbranch_vccnz .LBB0_1620
	v_and_b32_e32 v0, 60, v206
	v_lshl_add_u32 v4, s2, 5, v0
	s_movk_i32 s2, 0x4000
	v_cmp_gt_i32_e32 vcc, s2, v4
	s_and_saveexec_b64 s[2:3], vcc
	s_cbranch_execz .LBB0_1620
	v_lshlrev_b32_e32 v0, 3, v1
	v_and_b32_e32 v5, 0x1f8, v0
	v_lshlrev_b32_e32 v0, 1, v5
	v_mov_b32_e32 v1, 0
	s_load_dwordx4 s[4:7], s[0:1], 0xe0
	v_lshl_add_u64 v[2:3], s[66:67], 0, v[0:1]
	s_mov_b64 s[0:1], 0x1c00000
	v_lshl_add_u64 v[6:7], v[2:3], 0, s[0:1]
	v_mbcnt_lo_u32_b32 v2, -1, 0
	v_mbcnt_hi_u32_b32 v2, -1, v2
	v_and_b32_e32 v3, 64, v2
	v_lshlrev_b32_e32 v0, 2, v5
	v_add_u32_e32 v3, 64, v3
	v_xor_b32_e32 v5, 32, v2
	v_cmp_lt_i32_e32 vcc, v5, v3
	s_waitcnt lgkmcnt(0)
	v_lshl_add_u64 v[8:9], s[4:5], 0, v[0:1]
	s_mov_b32 s4, 0x3727c5ac
	v_cndmask_b32_e32 v5, v2, v5, vcc
	v_lshlrev_b32_e32 v48, 2, v5
	v_xor_b32_e32 v5, 16, v2
	v_cmp_lt_i32_e32 vcc, v5, v3
	s_lshl_b32 s3, s70, 5
	v_lshl_add_u64 v[10:11], s[6:7], 0, v[0:1]
	v_cndmask_b32_e32 v5, v2, v5, vcc
	v_lshlrev_b32_e32 v49, 2, v5
	v_xor_b32_e32 v5, 8, v2
	v_cmp_lt_i32_e32 vcc, v5, v3
	v_lshl_add_u64 v[12:13], s[64:65], 0, v[0:1]
	s_mov_b64 s[0:1], 0
	v_cndmask_b32_e32 v5, v2, v5, vcc
	v_lshlrev_b32_e32 v50, 2, v5
	v_xor_b32_e32 v5, 4, v2
	v_cmp_lt_i32_e32 vcc, v5, v3
	s_mov_b32 s2, 0x3a800000
	v_mov_b64_e32 v[14:15], s[4:5]
	v_cndmask_b32_e32 v5, v2, v5, vcc
	v_lshlrev_b32_e32 v51, 2, v5
	v_xor_b32_e32 v5, 2, v2
	v_cmp_lt_i32_e32 vcc, v5, v3
	s_mov_b32 s4, 0x800000
	s_movk_i32 s5, 0x3fff
	v_cndmask_b32_e32 v5, v2, v5, vcc
	v_lshlrev_b32_e32 v52, 2, v5
	v_xor_b32_e32 v5, 1, v2
	v_cmp_lt_i32_e32 vcc, v5, v3
	s_nop 1
	v_cndmask_b32_e32 v2, v2, v5, vcc
	v_lshlrev_b32_e32 v53, 2, v2
	global_load_dwordx4 v[112:115], v[10:11], off
	global_load_dwordx4 v[116:119], v[10:11], off offset:16
	global_load_dwordx4 v[120:123], v[10:11], off offset:2048
	global_load_dwordx4 v[124:127], v[10:11], off offset:2064
	global_load_dwordx4 v[128:131], v[8:9], off
	global_load_dwordx4 v[132:135], v[8:9], off offset:16
	global_load_dwordx4 v[136:139], v[8:9], off offset:2048
	global_load_dwordx4 v[140:143], v[8:9], off offset:2064
	s_mov_b64 s[14:15], 0x1000
	v_mov_b32_e32 v192, v4
	v_ashrrev_i32_e32 v193, 31, v192
	v_lshlrev_b64 v[194:195], 11, v[192:193]
	v_lshl_add_u64 v[194:195], v[6:7], 0, v[194:195]
	v_lshl_add_u64 v[196:197], v[194:195], 0, s[14:15]
	global_load_dwordx4 v[144:147], v[194:195], off
	global_load_dwordx4 v[148:151], v[194:195], off offset:1024
	global_load_dwordx4 v[152:155], v[194:195], off offset:2048
	global_load_dwordx4 v[156:159], v[194:195], off offset:3072
	global_load_dwordx4 v[160:163], v[196:197], off
	global_load_dwordx4 v[164:167], v[196:197], off offset:1024
	global_load_dwordx4 v[168:171], v[196:197], off offset:2048
	global_load_dwordx4 v[172:175], v[196:197], off offset:3072
	s_waitcnt vmcnt(0)
.LBB0_1619:
	v_ashrrev_i32_e32 v5, 31, v4
	v_lshlrev_b64 v[0:1], 11, v[4:5]
	v_add_u32_e32 v36, 1, v4
	v_lshl_add_u64 v[20:21], v[6:7], 0, v[0:1]
	v_ashrrev_i32_e32 v37, 31, v36
	v_lshlrev_b64 v[20:21], 11, v[36:37]
	v_lshl_add_u64 v[28:29], v[6:7], 0, v[20:21]
	v_mov_b32_e32 v54, v132
	v_mov_b32_e32 v55, v133
	v_mov_b32_e32 v56, v134
	v_mov_b32_e32 v57, v135
	v_mov_b32_e32 v58, v128
	v_mov_b32_e32 v59, v129
	v_mov_b32_e32 v60, v130
	v_mov_b32_e32 v61, v131
	v_mov_b32_e32 v62, v116
	v_mov_b32_e32 v63, v117
	v_mov_b32_e32 v64, v118
	v_mov_b32_e32 v65, v119
	v_mov_b32_e32 v66, v112
	v_mov_b32_e32 v67, v113
	v_mov_b32_e32 v68, v114
	v_mov_b32_e32 v69, v115
	v_lshlrev_b64 v[36:37], 12, v[36:37]
	v_lshl_add_u64 v[36:37], v[12:13], 0, v[36:37]
	s_waitcnt vmcnt(16)
	v_mov_b32_e32 v0, v144
	v_mov_b32_e32 v1, v145
	v_mov_b32_e32 v2, v146
	v_mov_b32_e32 v3, v147
	v_mov_b32_e32 v16, v148
	v_mov_b32_e32 v17, v149
	v_mov_b32_e32 v18, v150
	v_mov_b32_e32 v19, v151
	v_mov_b32_e32 v20, v152
	v_mov_b32_e32 v21, v153
	v_mov_b32_e32 v22, v154
	v_mov_b32_e32 v23, v155
	v_mov_b32_e32 v24, v156
	v_mov_b32_e32 v25, v157
	v_mov_b32_e32 v26, v158
	v_mov_b32_e32 v27, v159
	v_lshlrev_b32_e32 v30, 16, v0
	v_and_b32_e32 v31, 0xffff0000, v0
	v_add_f32_e32 v40, 0, v30
	v_lshlrev_b32_e32 v70, 16, v20
	v_lshlrev_b32_e32 v0, 16, v1
	v_and_b32_e32 v71, 0xffff0000, v20
	v_add_f32_e32 v40, v40, v31
	v_add_f32_e32 v41, 0, v70
	v_and_b32_e32 v1, 0xffff0000, v1
	v_lshlrev_b32_e32 v20, 16, v21
	v_add_f32_e32 v40, v40, v0
	v_add_f32_e32 v41, v41, v71
	v_lshlrev_b32_e32 v28, 16, v2
	v_and_b32_e32 v21, 0xffff0000, v21
	v_add_f32_e32 v40, v40, v1
	v_add_f32_e32 v41, v41, v20
	v_and_b32_e32 v29, 0xffff0000, v2
	v_lshlrev_b32_e32 v38, 16, v22
	v_add_f32_e32 v40, v40, v28
	v_add_f32_e32 v41, v41, v21
	v_lshlrev_b32_e32 v2, 16, v3
	v_and_b32_e32 v39, 0xffff0000, v22
	v_add_f32_e32 v40, v40, v29
	v_add_f32_e32 v41, v41, v38
	v_and_b32_e32 v3, 0xffff0000, v3
	v_lshlrev_b32_e32 v22, 16, v23
	v_add_f32_e32 v40, v40, v2
	v_add_f32_e32 v41, v41, v39
	v_lshlrev_b32_e32 v34, 16, v16
	v_and_b32_e32 v23, 0xffff0000, v23
	v_add_f32_e32 v40, v40, v3
	v_add_f32_e32 v41, v41, v22
	v_and_b32_e32 v35, 0xffff0000, v16
	v_lshlrev_b32_e32 v74, 16, v24
	v_add_f32_e32 v40, v40, v34
	v_add_f32_e32 v41, v41, v23
	v_lshlrev_b32_e32 v16, 16, v17
	v_and_b32_e32 v75, 0xffff0000, v24
	v_add_f32_e32 v40, v40, v35
	v_add_f32_e32 v41, v41, v74
	v_and_b32_e32 v17, 0xffff0000, v17
	v_lshlrev_b32_e32 v24, 16, v25
	v_add_f32_e32 v40, v40, v16
	v_add_f32_e32 v41, v41, v75
	v_lshlrev_b32_e32 v32, 16, v18
	v_and_b32_e32 v25, 0xffff0000, v25
	v_add_f32_e32 v40, v40, v17
	v_add_f32_e32 v41, v41, v24
	v_and_b32_e32 v33, 0xffff0000, v18
	v_lshlrev_b32_e32 v72, 16, v26
	v_add_f32_e32 v40, v40, v32
	v_add_f32_e32 v41, v41, v25
	v_lshlrev_b32_e32 v18, 16, v19
	v_and_b32_e32 v73, 0xffff0000, v26
	v_add_f32_e32 v40, v40, v33
	v_add_f32_e32 v41, v41, v72
	v_and_b32_e32 v19, 0xffff0000, v19
	v_lshlrev_b32_e32 v26, 16, v27
	v_add_f32_e32 v40, v40, v18
	v_add_f32_e32 v41, v41, v73
	v_and_b32_e32 v27, 0xffff0000, v27
	v_add_f32_e32 v40, v40, v19
	v_add_f32_e32 v41, v41, v26
	ds_bpermute_b32 v42, v48, v40
	v_add_f32_e32 v41, v41, v27
	ds_bpermute_b32 v43, v48, v41
	s_waitcnt lgkmcnt(1)
	v_add_f32_e32 v40, v40, v42
	ds_bpermute_b32 v42, v49, v40
	s_waitcnt lgkmcnt(1)
	v_add_f32_e32 v41, v41, v43
	ds_bpermute_b32 v43, v49, v41
	s_waitcnt lgkmcnt(1)
	v_add_f32_e32 v40, v40, v42
	ds_bpermute_b32 v42, v50, v40
	s_waitcnt lgkmcnt(1)
	v_add_f32_e32 v41, v41, v43
	ds_bpermute_b32 v43, v50, v41
	s_waitcnt lgkmcnt(1)
	v_add_f32_e32 v40, v40, v42
	ds_bpermute_b32 v42, v51, v40
	s_waitcnt lgkmcnt(1)
	v_add_f32_e32 v41, v41, v43
	ds_bpermute_b32 v43, v51, v41
	s_waitcnt lgkmcnt(1)
	v_add_f32_e32 v40, v40, v42
	ds_bpermute_b32 v42, v52, v40
	s_waitcnt lgkmcnt(1)
	v_add_f32_e32 v41, v41, v43
	ds_bpermute_b32 v43, v52, v41
	s_waitcnt lgkmcnt(1)
	v_add_f32_e32 v40, v40, v42
	ds_bpermute_b32 v42, v53, v40
	s_waitcnt lgkmcnt(1)
	v_add_f32_e32 v41, v41, v43
	ds_bpermute_b32 v43, v53, v41
	s_waitcnt lgkmcnt(1)
	v_add_f32_e32 v40, v40, v42
	v_mul_f32_e32 v46, 0x3a800000, v40
	s_waitcnt lgkmcnt(0)
	v_add_f32_e32 v76, v41, v43
	v_pk_add_f32 v[84:85], v[0:1], v[46:47] op_sel_hi:[1,0] neg_lo:[0,1] neg_hi:[0,1]
	v_mul_f32_e32 v0, 0x3a800000, v76
	v_pk_add_f32 v[82:83], v[30:31], v[46:47] op_sel_hi:[1,0] neg_lo:[0,1] neg_hi:[0,1]
	v_pk_add_f32 v[86:87], v[28:29], v[46:47] op_sel_hi:[1,0] neg_lo:[0,1] neg_hi:[0,1]
	v_pk_add_f32 v[28:29], v[70:71], v[0:1] op_sel_hi:[1,0] neg_lo:[0,1] neg_hi:[0,1]
	v_mov_b32_e32 v77, v83
	v_mov_b32_e32 v76, v29
	v_mov_b32_e32 v71, v82
	v_pk_add_f32 v[30:31], v[20:21], v[0:1] op_sel_hi:[1,0] neg_lo:[0,1] neg_hi:[0,1]
	v_mov_b32_e32 v70, v28
	v_pk_mul_f32 v[76:77], v[76:77], v[76:77]
	v_mov_b32_e32 v79, v84
	v_mov_b32_e32 v78, v30
	v_pk_fma_f32 v[70:71], v[70:71], v[70:71], v[76:77]
	v_pk_add_f32 v[40:41], v[34:35], v[46:47] op_sel_hi:[1,0] neg_lo:[0,1] neg_hi:[0,1]
	v_pk_add_f32 v[42:43], v[32:33], v[46:47] op_sel_hi:[1,0] neg_lo:[0,1] neg_hi:[0,1]
	v_pk_add_f32 v[32:33], v[38:39], v[0:1] op_sel_hi:[1,0] neg_lo:[0,1] neg_hi:[0,1]
	v_pk_add_f32 v[34:35], v[22:23], v[0:1] op_sel_hi:[1,0] neg_lo:[0,1] neg_hi:[0,1]
	v_pk_add_f32 v[22:23], v[24:25], v[0:1] op_sel_hi:[1,0] neg_lo:[0,1] neg_hi:[0,1]
	v_mov_b32_e32 v25, v85
	v_mov_b32_e32 v24, v31
	v_pk_fma_f32 v[70:71], v[78:79], v[78:79], v[70:71]
	v_mov_b32_e32 v39, v86
	v_mov_b32_e32 v38, v32
	v_pk_fma_f32 v[24:25], v[24:25], v[24:25], v[70:71]
	v_pk_add_f32 v[88:89], v[2:3], v[46:47] op_sel_hi:[1,0] neg_lo:[0,1] neg_hi:[0,1]
	v_pk_add_f32 v[20:21], v[72:73], v[0:1] op_sel_hi:[1,0] neg_lo:[0,1] neg_hi:[0,1]
	v_mov_b32_e32 v73, v87
	v_mov_b32_e32 v72, v33
	v_pk_fma_f32 v[24:25], v[38:39], v[38:39], v[24:25]
	v_pk_add_f32 v[44:45], v[16:17], v[46:47] op_sel_hi:[1,0] neg_lo:[0,1] neg_hi:[0,1]
	v_pk_add_f32 v[46:47], v[18:19], v[46:47] op_sel_hi:[1,0] neg_lo:[0,1] neg_hi:[0,1]
	v_pk_add_f32 v[18:19], v[74:75], v[0:1] op_sel_hi:[1,0] neg_lo:[0,1] neg_hi:[0,1]
	v_mov_b32_e32 v75, v88
	v_mov_b32_e32 v74, v34
	v_pk_fma_f32 v[24:25], v[72:73], v[72:73], v[24:25]
	v_mov_b32_e32 v81, v89
	v_mov_b32_e32 v80, v35
	v_pk_fma_f32 v[24:25], v[74:75], v[74:75], v[24:25]
	v_mov_b32_e32 v92, v18
	v_pk_fma_f32 v[24:25], v[80:81], v[80:81], v[24:25]
	v_mov_b32_e32 v93, v40
	v_pk_fma_f32 v[24:25], v[92:93], v[92:93], v[24:25]
	v_mov_b32_e32 v38, v19
	v_mov_b32_e32 v39, v41
	v_pk_fma_f32 v[24:25], v[38:39], v[38:39], v[24:25]
	v_mov_b32_e32 v38, v22
	v_mov_b32_e32 v39, v44
	v_pk_mul_f32 v[2:3], v[42:43], v[42:43]
	v_pk_mul_f32 v[90:91], v[20:21], v[20:21]
	v_pk_fma_f32 v[24:25], v[38:39], v[38:39], v[24:25]
	v_mov_b32_e32 v38, v23
	v_mov_b32_e32 v39, v45
	v_pk_fma_f32 v[24:25], v[38:39], v[38:39], v[24:25]
	v_mov_b32_e32 v38, v90
	v_mov_b32_e32 v39, v2
	v_pk_add_f32 v[26:27], v[26:27], v[0:1] op_sel_hi:[1,0] neg_lo:[0,1] neg_hi:[0,1]
	v_pk_mul_f32 v[16:17], v[46:47], v[46:47]
	v_pk_add_f32 v[24:25], v[38:39], v[24:25]
	v_pk_mul_f32 v[0:1], v[26:27], v[26:27]
	v_mov_b32_e32 v2, v91
	v_pk_add_f32 v[2:3], v[2:3], v[24:25]
	v_mov_b32_e32 v24, v0
	v_mov_b32_e32 v25, v16
	v_pk_add_f32 v[2:3], v[24:25], v[2:3]
	v_mov_b32_e32 v16, v1
	v_pk_add_f32 v[0:1], v[16:17], v[2:3]
	ds_bpermute_b32 v3, v48, v1
	ds_bpermute_b32 v2, v48, v0
	v_add_u32_e32 v24, 2, v4
	v_ashrrev_i32_e32 v25, 31, v24
	v_lshlrev_b64 v[16:17], 11, v[24:25]
	v_lshl_add_u64 v[16:17], v[6:7], 0, v[16:17]
	s_waitcnt lgkmcnt(0)
	v_pk_add_f32 v[0:1], v[0:1], v[2:3]
	ds_bpermute_b32 v3, v49, v1
	ds_bpermute_b32 v2, v49, v0
	v_mov_b32_e32 v70, v160
	v_mov_b32_e32 v71, v161
	v_mov_b32_e32 v72, v162
	v_mov_b32_e32 v73, v163
	v_mov_b32_e32 v74, v164
	v_mov_b32_e32 v75, v165
	v_mov_b32_e32 v76, v166
	v_mov_b32_e32 v77, v167
	v_add_u32_e32 v16, 3, v4
	v_ashrrev_i32_e32 v17, 31, v16
	v_lshlrev_b64 v[38:39], 11, v[16:17]
	s_waitcnt lgkmcnt(0)
	v_pk_add_f32 v[0:1], v[0:1], v[2:3]
	ds_bpermute_b32 v3, v50, v1
	ds_bpermute_b32 v2, v50, v0
	v_lshl_add_u64 v[90:91], v[6:7], 0, v[38:39]
	v_lshlrev_b64 v[16:17], 12, v[16:17]
	s_waitcnt lgkmcnt(0)
	v_pk_add_f32 v[0:1], v[0:1], v[2:3]
	ds_bpermute_b32 v3, v51, v1
	ds_bpermute_b32 v2, v51, v0
	s_waitcnt lgkmcnt(0)
	v_pk_add_f32 v[0:1], v[0:1], v[2:3]
	ds_bpermute_b32 v3, v52, v1
	ds_bpermute_b32 v2, v52, v0
	s_waitcnt lgkmcnt(0)
	v_pk_add_f32 v[0:1], v[0:1], v[2:3]
	ds_bpermute_b32 v3, v53, v1
	ds_bpermute_b32 v2, v53, v0
	s_waitcnt lgkmcnt(0)
	v_pk_add_f32 v[0:1], v[0:1], v[2:3]
	s_nop 0
	v_pk_fma_f32 v[38:39], v[0:1], s[2:3], v[14:15] op_sel_hi:[1,0,0]
	s_nop 0
	v_mul_f32_e32 v0, 0x4b800000, v39
	v_cmp_gt_f32_e32 vcc, s4, v39
	s_nop 1
	v_cndmask_b32_e32 v0, v39, v0, vcc
	v_rsq_f32_e32 v39, v0
	v_mov_b32_e32 v78, v168
	v_mov_b32_e32 v79, v169
	v_mov_b32_e32 v80, v170
	v_mov_b32_e32 v81, v171
	v_mov_b32_e32 v0, v172
	v_mov_b32_e32 v1, v173
	v_mov_b32_e32 v2, v174
	v_mov_b32_e32 v3, v175
	v_add_u32_e32 v192, s3, v4
	v_cmp_ge_i32_e64 s[8:9], s5, v192
	s_and_saveexec_b64 s[12:13], s[8:9]
	v_ashrrev_i32_e32 v193, 31, v192
	v_lshlrev_b64 v[194:195], 11, v[192:193]
	v_lshl_add_u64 v[194:195], v[6:7], 0, v[194:195]
	v_lshl_add_u64 v[196:197], v[194:195], 0, s[14:15]
	global_load_dwordx4 v[144:147], v[194:195], off
	global_load_dwordx4 v[148:151], v[194:195], off offset:1024
	global_load_dwordx4 v[152:155], v[194:195], off offset:2048
	global_load_dwordx4 v[156:159], v[194:195], off offset:3072
	global_load_dwordx4 v[160:163], v[196:197], off
	global_load_dwordx4 v[164:167], v[196:197], off offset:1024
	global_load_dwordx4 v[168:171], v[196:197], off offset:2048
	global_load_dwordx4 v[172:175], v[196:197], off offset:3072
	s_mov_b64 exec, s[12:13]
	v_lshlrev_b64 v[90:91], 12, v[4:5]
	v_lshl_add_u64 v[90:91], v[12:13], 0, v[90:91]
	v_mul_f32_e32 v5, 0x45800000, v39
	v_cndmask_b32_e32 v92, v39, v5, vcc
	v_pk_mul_f32 v[82:83], v[82:83], v[92:93] op_sel_hi:[1,0]
	v_pk_mul_f32 v[84:85], v[84:85], v[92:93] op_sel_hi:[1,0]
	v_pk_fma_f32 v[58:59], v[58:59], v[82:83], v[66:67]
	v_pk_fma_f32 v[60:61], v[60:61], v[84:85], v[68:69]
	v_pk_mul_f32 v[66:67], v[86:87], v[92:93] op_sel_hi:[1,0]
	v_pk_mul_f32 v[68:69], v[88:89], v[92:93] op_sel_hi:[1,0]
	v_pk_fma_f32 v[54:55], v[54:55], v[66:67], v[62:63]
	v_pk_fma_f32 v[56:57], v[56:57], v[68:69], v[64:65]
	global_store_dwordx4 v[90:91], v[58:61], off
	global_store_dwordx4 v[90:91], v[54:57], off offset:16
	s_nop 1
	v_mov_b32_e32 v54, v120
	v_mov_b32_e32 v55, v121
	v_mov_b32_e32 v56, v122
	v_mov_b32_e32 v57, v123
	s_nop 0
	v_mov_b32_e32 v58, v136
	v_mov_b32_e32 v59, v137
	v_mov_b32_e32 v60, v138
	v_mov_b32_e32 v61, v139
	v_mov_b32_e32 v62, v140
	v_mov_b32_e32 v63, v141
	v_mov_b32_e32 v64, v142
	v_mov_b32_e32 v65, v143
	v_mov_b32_e32 v66, v124
	v_mov_b32_e32 v67, v125
	v_mov_b32_e32 v68, v126
	v_mov_b32_e32 v69, v127
	v_pk_mul_f32 v[44:45], v[44:45], v[92:93] op_sel_hi:[1,0]
	v_pk_mul_f32 v[40:41], v[40:41], v[92:93] op_sel_hi:[1,0]
	v_pk_mul_f32 v[46:47], v[46:47], v[92:93] op_sel_hi:[1,0]
	v_pk_mul_f32 v[84:85], v[42:43], v[92:93] op_sel_hi:[1,0]
	v_cmp_gt_f32_e32 vcc, s4, v38
	v_add_u32_e32 v4, s3, v4
	v_lshlrev_b32_e32 v82, 16, v72
	v_and_b32_e32 v83, 0xffff0000, v72
	v_lshlrev_b32_e32 v72, 16, v74
	v_lshlrev_b32_e32 v92, 16, v1
	v_and_b32_e32 v93, 0xffff0000, v1
	v_lshlrev_b32_e32 v86, 16, v2
	v_and_b32_e32 v87, 0xffff0000, v2
	v_lshlrev_b32_e32 v88, 16, v3
	v_and_b32_e32 v89, 0xffff0000, v3
	v_pk_fma_f32 v[40:41], v[58:59], v[40:41], v[54:55]
	v_pk_fma_f32 v[42:43], v[60:61], v[44:45], v[56:57]
	v_pk_fma_f32 v[44:45], v[62:63], v[84:85], v[66:67]
	v_pk_fma_f32 v[46:47], v[64:65], v[46:47], v[68:69]
	global_store_dwordx4 v[90:91], v[40:43], off offset:2048
	global_store_dwordx4 v[90:91], v[44:47], off offset:2064
	s_nop 0
	v_mov_b32_e32 v40, v132
	v_mov_b32_e32 v41, v133
	v_mov_b32_e32 v42, v134
	v_mov_b32_e32 v43, v135
	s_nop 0
	v_mov_b32_e32 v44, v128
	v_mov_b32_e32 v45, v129
	v_mov_b32_e32 v46, v130
	v_mov_b32_e32 v47, v131
	v_mov_b32_e32 v54, v116
	v_mov_b32_e32 v55, v117
	v_mov_b32_e32 v56, v118
	v_mov_b32_e32 v57, v119
	v_mov_b32_e32 v58, v112
	v_mov_b32_e32 v59, v113
	v_mov_b32_e32 v60, v114
	v_mov_b32_e32 v61, v115
	v_lshlrev_b32_e32 v64, 16, v70
	v_and_b32_e32 v65, 0xffff0000, v70
	v_lshlrev_b32_e32 v90, 16, v0
	v_and_b32_e32 v91, 0xffff0000, v0
	v_add_f32_e32 v0, 0, v64
	v_lshlrev_b32_e32 v66, 16, v71
	v_add_f32_e32 v0, v0, v65
	v_and_b32_e32 v67, 0xffff0000, v71
	v_add_f32_e32 v0, v0, v66
	v_add_f32_e32 v0, v0, v67
	v_add_f32_e32 v0, v0, v82
	v_lshlrev_b32_e32 v62, 16, v73
	v_lshlrev_b32_e32 v84, 16, v78
	v_add_f32_e32 v0, v0, v83
	v_and_b32_e32 v63, 0xffff0000, v73
	v_and_b32_e32 v85, 0xffff0000, v78
	v_add_f32_e32 v1, 0, v84
	v_add_f32_e32 v0, v0, v62
	v_lshlrev_b32_e32 v78, 16, v79
	v_add_f32_e32 v1, v1, v85
	v_add_f32_e32 v0, v0, v63
	v_and_b32_e32 v73, 0xffff0000, v74
	v_and_b32_e32 v79, 0xffff0000, v79
	v_add_f32_e32 v1, v1, v78
	v_add_f32_e32 v0, v0, v72
	v_lshlrev_b32_e32 v68, 16, v76
	v_and_b32_e32 v69, 0xffff0000, v76
	v_lshlrev_b32_e32 v74, 16, v75
	v_lshlrev_b32_e32 v76, 16, v80
	v_add_f32_e32 v1, v1, v79
	v_add_f32_e32 v0, v0, v73
	v_lshlrev_b32_e32 v70, 16, v77
	v_and_b32_e32 v71, 0xffff0000, v77
	v_and_b32_e32 v75, 0xffff0000, v75
	v_and_b32_e32 v77, 0xffff0000, v80
	v_add_f32_e32 v1, v1, v76
	v_add_f32_e32 v0, v0, v74
	v_lshlrev_b32_e32 v80, 16, v81
	v_add_f32_e32 v1, v1, v77
	v_add_f32_e32 v0, v0, v75
	v_and_b32_e32 v81, 0xffff0000, v81
	v_add_f32_e32 v1, v1, v80
	v_add_f32_e32 v0, v0, v68
	v_add_f32_e32 v1, v1, v81
	v_add_f32_e32 v0, v0, v69
	v_add_f32_e32 v1, v1, v90
	v_add_f32_e32 v0, v0, v70
	v_add_f32_e32 v1, v1, v91
	v_add_f32_e32 v0, v0, v71
	v_add_f32_e32 v1, v1, v92
	ds_bpermute_b32 v2, v48, v0
	v_add_f32_e32 v1, v1, v93
	v_add_f32_e32 v1, v1, v86
	v_add_f32_e32 v1, v1, v87
	v_add_f32_e32 v1, v1, v88
	v_add_f32_e32 v1, v1, v89
	s_waitcnt lgkmcnt(0)
	v_add_f32_e32 v5, v0, v2
	v_mul_f32_e32 v0, 0x4b800000, v38
	ds_bpermute_b32 v3, v48, v1
	v_cndmask_b32_e32 v0, v38, v0, vcc
	v_rsq_f32_e32 v0, v0
	ds_bpermute_b32 v96, v49, v5
	s_waitcnt lgkmcnt(1)
	v_add_f32_e32 v95, v1, v3
	v_mul_f32_e32 v1, 0x45800000, v0
	v_cndmask_b32_e32 v94, v0, v1, vcc
	v_pk_mul_f32 v[2:3], v[30:31], v[94:95] op_sel_hi:[1,0]
	v_pk_mul_f32 v[0:1], v[28:29], v[94:95] op_sel_hi:[1,0]
	v_pk_mul_f32 v[30:31], v[34:35], v[94:95] op_sel_hi:[1,0]
	v_pk_mul_f32 v[28:29], v[32:33], v[94:95] op_sel_hi:[1,0]
	ds_bpermute_b32 v97, v49, v95
	v_pk_mul_f32 v[22:23], v[22:23], v[94:95] op_sel_hi:[1,0]
	v_pk_mul_f32 v[18:19], v[18:19], v[94:95] op_sel_hi:[1,0]
	v_pk_mul_f32 v[26:27], v[26:27], v[94:95] op_sel_hi:[1,0]
	v_pk_fma_f32 v[28:29], v[40:41], v[28:29], v[54:55]
	v_pk_fma_f32 v[0:1], v[44:45], v[0:1], v[58:59]
	v_pk_fma_f32 v[2:3], v[46:47], v[2:3], v[60:61]
	v_pk_fma_f32 v[30:31], v[42:43], v[30:31], v[56:57]
	global_store_dwordx4 v[36:37], v[0:3], off
	global_store_dwordx4 v[36:37], v[28:31], off offset:16
	v_mov_b32_e32 v32, v140
	v_mov_b32_e32 v33, v141
	v_mov_b32_e32 v34, v142
	v_mov_b32_e32 v35, v143
	v_mov_b32_e32 v38, v136
	v_mov_b32_e32 v39, v137
	v_mov_b32_e32 v40, v138
	v_mov_b32_e32 v41, v139
	v_mov_b32_e32 v42, v124
	v_mov_b32_e32 v43, v125
	v_mov_b32_e32 v44, v126
	v_mov_b32_e32 v45, v127
	v_mov_b32_e32 v54, v120
	v_mov_b32_e32 v55, v121
	v_mov_b32_e32 v56, v122
	v_mov_b32_e32 v57, v123
	s_waitcnt lgkmcnt(1)
	v_add_f32_e32 v0, v5, v96
	s_waitcnt lgkmcnt(0)
	v_add_f32_e32 v1, v95, v97
	ds_bpermute_b32 v2, v50, v0
	ds_bpermute_b32 v3, v50, v1
	v_pk_mul_f32 v[94:95], v[20:21], v[94:95] op_sel_hi:[1,0]
	s_waitcnt lgkmcnt(1)
	v_add_f32_e32 v0, v0, v2
	s_waitcnt lgkmcnt(0)
	v_add_f32_e32 v1, v1, v3
	ds_bpermute_b32 v2, v51, v0
	ds_bpermute_b32 v3, v51, v1
	s_waitcnt lgkmcnt(1)
	v_add_f32_e32 v0, v0, v2
	s_waitcnt lgkmcnt(0)
	v_add_f32_e32 v1, v1, v3
	ds_bpermute_b32 v2, v52, v0
	ds_bpermute_b32 v3, v52, v1
	s_waitcnt lgkmcnt(1)
	v_add_f32_e32 v0, v0, v2
	s_waitcnt lgkmcnt(0)
	v_add_f32_e32 v1, v1, v3
	ds_bpermute_b32 v2, v53, v0
	ds_bpermute_b32 v3, v53, v1
	s_waitcnt lgkmcnt(1)
	v_add_f32_e32 v0, v0, v2
	s_waitcnt lgkmcnt(0)
	v_add_f32_e32 v1, v1, v3
	v_mul_f32_e32 v0, 0x3a800000, v0
	v_mul_f32_e32 v30, 0x3a800000, v1
	v_pk_add_f32 v[46:47], v[64:65], v[0:1] op_sel_hi:[1,0] neg_lo:[0,1] neg_hi:[0,1]
	v_pk_add_f32 v[64:65], v[72:73], v[0:1] op_sel_hi:[1,0] neg_lo:[0,1] neg_hi:[0,1]
	v_pk_add_f32 v[72:73], v[84:85], v[30:31] op_sel_hi:[1,0] neg_lo:[0,1] neg_hi:[0,1]
	v_pk_add_f32 v[58:59], v[66:67], v[0:1] op_sel_hi:[1,0] neg_lo:[0,1] neg_hi:[0,1]
	v_pk_add_f32 v[60:61], v[82:83], v[0:1] op_sel_hi:[1,0] neg_lo:[0,1] neg_hi:[0,1]
	v_pk_add_f32 v[62:63], v[62:63], v[0:1] op_sel_hi:[1,0] neg_lo:[0,1] neg_hi:[0,1]
	v_pk_add_f32 v[66:67], v[74:75], v[0:1] op_sel_hi:[1,0] neg_lo:[0,1] neg_hi:[0,1]
	v_pk_add_f32 v[68:69], v[68:69], v[0:1] op_sel_hi:[1,0] neg_lo:[0,1] neg_hi:[0,1]
	v_pk_add_f32 v[70:71], v[70:71], v[0:1] op_sel_hi:[1,0] neg_lo:[0,1] neg_hi:[0,1]
	v_pk_add_f32 v[74:75], v[78:79], v[30:31] op_sel_hi:[1,0] neg_lo:[0,1] neg_hi:[0,1]
	v_pk_add_f32 v[76:77], v[76:77], v[30:31] op_sel_hi:[1,0] neg_lo:[0,1] neg_hi:[0,1]
	v_pk_add_f32 v[78:79], v[80:81], v[30:31] op_sel_hi:[1,0] neg_lo:[0,1] neg_hi:[0,1]
	v_pk_add_f32 v[0:1], v[90:91], v[30:31] op_sel_hi:[1,0] neg_lo:[0,1] neg_hi:[0,1]
	v_pk_add_f32 v[28:29], v[92:93], v[30:31] op_sel_hi:[1,0] neg_lo:[0,1] neg_hi:[0,1]
	v_pk_add_f32 v[2:3], v[86:87], v[30:31] op_sel_hi:[1,0] neg_lo:[0,1] neg_hi:[0,1]
	v_pk_add_f32 v[30:31], v[88:89], v[30:31] op_sel_hi:[1,0] neg_lo:[0,1] neg_hi:[0,1]
	v_mov_b32_e32 v86, v73
	v_mov_b32_e32 v87, v47
	v_pk_mul_f32 v[82:83], v[70:71], v[70:71]
	v_mov_b32_e32 v84, v72
	v_mov_b32_e32 v85, v46
	v_mov_b32_e32 v88, v74
	v_mov_b32_e32 v89, v58
	v_mov_b32_e32 v92, v75
	v_mov_b32_e32 v93, v59
	v_mov_b32_e32 v96, v76
	v_mov_b32_e32 v97, v60
	v_mov_b32_e32 v98, v77
	v_mov_b32_e32 v99, v61
	v_mov_b32_e32 v100, v78
	v_mov_b32_e32 v101, v62
	v_mov_b32_e32 v102, v79
	v_mov_b32_e32 v103, v63
	v_mov_b32_e32 v104, v0
	v_mov_b32_e32 v105, v64
	v_mov_b32_e32 v106, v1
	v_mov_b32_e32 v107, v65
	v_mov_b32_e32 v108, v28
	v_mov_b32_e32 v109, v66
	v_pk_mul_f32 v[80:81], v[68:69], v[68:69]
	v_pk_mul_f32 v[90:91], v[2:3], v[2:3]
	v_mov_b32_e32 v110, v29
	v_mov_b32_e32 v111, v67
	v_pk_fma_f32 v[32:33], v[32:33], v[94:95], v[42:43]
	v_pk_fma_f32 v[18:19], v[38:39], v[18:19], v[54:55]
	v_pk_fma_f32 v[20:21], v[40:41], v[22:23], v[56:57]
	v_pk_fma_f32 v[34:35], v[34:35], v[26:27], v[44:45]
	global_store_dwordx4 v[36:37], v[18:21], off offset:2048
	global_store_dwordx4 v[36:37], v[32:35], off offset:2064
	s_nop 0
	v_mov_b32_e32 v18, v132
	v_mov_b32_e32 v19, v133
	v_mov_b32_e32 v20, v134
	v_mov_b32_e32 v21, v135
	s_nop 0
	v_mov_b32_e32 v32, v128
	v_mov_b32_e32 v33, v129
	v_mov_b32_e32 v34, v130
	v_mov_b32_e32 v35, v131
	v_mov_b32_e32 v36, v116
	v_mov_b32_e32 v37, v117
	v_mov_b32_e32 v38, v118
	v_mov_b32_e32 v39, v119
	v_mov_b32_e32 v40, v112
	v_mov_b32_e32 v41, v113
	v_mov_b32_e32 v42, v114
	v_mov_b32_e32 v43, v115
	v_pk_mul_f32 v[22:23], v[30:31], v[30:31]
	v_pk_mul_f32 v[26:27], v[86:87], v[86:87]
	v_mov_b32_e32 v54, v22
	v_mov_b32_e32 v55, v82
	v_mov_b32_e32 v82, v23
	v_pk_fma_f32 v[22:23], v[84:85], v[84:85], v[26:27]
	v_mov_b32_e32 v44, v90
	v_pk_fma_f32 v[22:23], v[88:89], v[88:89], v[22:23]
	v_mov_b32_e32 v45, v80
	v_pk_fma_f32 v[22:23], v[92:93], v[92:93], v[22:23]
	v_mov_b32_e32 v80, v91
	v_pk_fma_f32 v[22:23], v[96:97], v[96:97], v[22:23]
	s_nop 0
	v_pk_fma_f32 v[22:23], v[98:99], v[98:99], v[22:23]
	s_nop 0
	v_pk_fma_f32 v[22:23], v[100:101], v[100:101], v[22:23]
	s_nop 0
	v_pk_fma_f32 v[22:23], v[102:103], v[102:103], v[22:23]
	s_nop 0
	v_pk_fma_f32 v[22:23], v[104:105], v[104:105], v[22:23]
	s_nop 0
	v_pk_fma_f32 v[22:23], v[106:107], v[106:107], v[22:23]
	s_nop 0
	v_pk_fma_f32 v[22:23], v[108:109], v[108:109], v[22:23]
	s_nop 0
	v_pk_fma_f32 v[22:23], v[110:111], v[110:111], v[22:23]
	s_nop 0
	v_pk_add_f32 v[22:23], v[44:45], v[22:23]
	s_nop 0
	v_pk_add_f32 v[22:23], v[80:81], v[22:23]
	s_nop 0
	v_pk_add_f32 v[22:23], v[54:55], v[22:23]
	s_nop 0
	v_pk_add_f32 v[22:23], v[82:83], v[22:23]
	ds_bpermute_b32 v27, v48, v23
	ds_bpermute_b32 v26, v48, v22
	s_waitcnt lgkmcnt(0)
	v_pk_add_f32 v[22:23], v[22:23], v[26:27]
	ds_bpermute_b32 v27, v49, v23
	ds_bpermute_b32 v26, v49, v22
	s_waitcnt lgkmcnt(0)
	v_pk_add_f32 v[22:23], v[22:23], v[26:27]
	ds_bpermute_b32 v27, v50, v23
	ds_bpermute_b32 v26, v50, v22
	s_waitcnt lgkmcnt(0)
	v_pk_add_f32 v[22:23], v[22:23], v[26:27]
	ds_bpermute_b32 v27, v51, v23
	ds_bpermute_b32 v26, v51, v22
	s_waitcnt lgkmcnt(0)
	v_pk_add_f32 v[22:23], v[22:23], v[26:27]
	ds_bpermute_b32 v27, v52, v23
	ds_bpermute_b32 v26, v52, v22
	s_waitcnt lgkmcnt(0)
	v_pk_add_f32 v[22:23], v[22:23], v[26:27]
	ds_bpermute_b32 v27, v53, v23
	ds_bpermute_b32 v26, v53, v22
	s_waitcnt lgkmcnt(0)
	v_pk_add_f32 v[22:23], v[22:23], v[26:27]
	s_nop 0
	v_pk_fma_f32 v[26:27], v[22:23], s[2:3], v[14:15] op_sel_hi:[1,0,0]
	v_lshlrev_b64 v[22:23], 12, v[24:25]
	v_mul_f32_e32 v5, 0x4b800000, v27
	v_cmp_gt_f32_e32 vcc, s4, v27
	v_lshl_add_u64 v[44:45], v[12:13], 0, v[22:23]
	s_nop 0
	v_cndmask_b32_e32 v5, v27, v5, vcc
	v_rsq_f32_e32 v5, v5
	s_nop 0
	v_mul_f32_e32 v22, 0x45800000, v5
	v_cndmask_b32_e32 v54, v5, v22, vcc
	v_pk_mul_f32 v[24:25], v[58:59], v[54:55] op_sel_hi:[1,0]
	v_pk_mul_f32 v[22:23], v[46:47], v[54:55] op_sel_hi:[1,0]
	v_pk_mul_f32 v[46:47], v[62:63], v[54:55] op_sel_hi:[1,0]
	v_pk_mul_f32 v[56:57], v[60:61], v[54:55] op_sel_hi:[1,0]
	v_pk_fma_f32 v[22:23], v[32:33], v[22:23], v[40:41]
	v_pk_fma_f32 v[24:25], v[34:35], v[24:25], v[42:43]
	v_pk_fma_f32 v[18:19], v[18:19], v[56:57], v[36:37]
	v_pk_fma_f32 v[20:21], v[20:21], v[46:47], v[38:39]
	global_store_dwordx4 v[44:45], v[22:25], off
	global_store_dwordx4 v[44:45], v[18:21], off offset:16
	s_nop 1
	v_mov_b32_e32 v18, v120
	v_mov_b32_e32 v19, v121
	v_mov_b32_e32 v20, v122
	v_mov_b32_e32 v21, v123
	s_nop 0
	v_mov_b32_e32 v22, v136
	v_mov_b32_e32 v23, v137
	v_mov_b32_e32 v24, v138
	v_mov_b32_e32 v25, v139
	v_mov_b32_e32 v32, v140
	v_mov_b32_e32 v33, v141
	v_mov_b32_e32 v34, v142
	v_mov_b32_e32 v35, v143
	v_mov_b32_e32 v36, v124
	v_mov_b32_e32 v37, v125
	v_mov_b32_e32 v38, v126
	v_mov_b32_e32 v39, v127
	v_pk_mul_f32 v[40:41], v[66:67], v[54:55] op_sel_hi:[1,0]
	v_pk_mul_f32 v[42:43], v[64:65], v[54:55] op_sel_hi:[1,0]
	v_pk_mul_f32 v[46:47], v[70:71], v[54:55] op_sel_hi:[1,0]
	v_pk_mul_f32 v[54:55], v[68:69], v[54:55] op_sel_hi:[1,0]
	v_mul_f32_e32 v5, 0x4b800000, v26
	v_cmp_gt_f32_e32 vcc, s4, v26
	v_pk_fma_f32 v[18:19], v[22:23], v[42:43], v[18:19]
	v_pk_fma_f32 v[20:21], v[24:25], v[40:41], v[20:21]
	v_pk_fma_f32 v[22:23], v[32:33], v[54:55], v[36:37]
	v_pk_fma_f32 v[24:25], v[34:35], v[46:47], v[38:39]
	global_store_dwordx4 v[44:45], v[18:21], off offset:2048
	global_store_dwordx4 v[44:45], v[22:25], off offset:2064
	s_nop 0
	v_mov_b32_e32 v18, v112
	v_mov_b32_e32 v19, v113
	v_mov_b32_e32 v20, v114
	v_mov_b32_e32 v21, v115
	s_nop 0
	v_mov_b32_e32 v22, v128
	v_mov_b32_e32 v23, v129
	v_mov_b32_e32 v24, v130
	v_mov_b32_e32 v25, v131
	v_mov_b32_e32 v32, v132
	v_mov_b32_e32 v33, v133
	v_mov_b32_e32 v34, v134
	v_mov_b32_e32 v35, v135
	v_mov_b32_e32 v36, v116
	v_mov_b32_e32 v37, v117
	v_mov_b32_e32 v38, v118
	v_mov_b32_e32 v39, v119
	v_cndmask_b32_e32 v5, v26, v5, vcc
	v_rsq_f32_e32 v5, v5
	v_lshl_add_u64 v[40:41], v[12:13], 0, v[16:17]
	v_mul_f32_e32 v16, 0x45800000, v5
	v_cndmask_b32_e32 v42, v5, v16, vcc
	v_pk_mul_f32 v[26:27], v[74:75], v[42:43] op_sel_hi:[1,0]
	v_pk_mul_f32 v[16:17], v[72:73], v[42:43] op_sel_hi:[1,0]
	v_pk_mul_f32 v[44:45], v[78:79], v[42:43] op_sel_hi:[1,0]
	v_pk_mul_f32 v[46:47], v[76:77], v[42:43] op_sel_hi:[1,0]
	v_cmp_lt_i32_e32 vcc, s5, v4
	v_pk_mul_f32 v[28:29], v[28:29], v[42:43] op_sel_hi:[1,0]
	v_pk_mul_f32 v[0:1], v[0:1], v[42:43] op_sel_hi:[1,0]
	s_or_b64 s[0:1], vcc, s[0:1]
	v_pk_mul_f32 v[30:31], v[30:31], v[42:43] op_sel_hi:[1,0]
	v_pk_fma_f32 v[16:17], v[22:23], v[16:17], v[18:19]
	v_pk_fma_f32 v[18:19], v[24:25], v[26:27], v[20:21]
	v_pk_fma_f32 v[20:21], v[32:33], v[46:47], v[36:37]
	v_pk_fma_f32 v[22:23], v[34:35], v[44:45], v[38:39]
	global_store_dwordx4 v[40:41], v[16:19], off
	global_store_dwordx4 v[40:41], v[20:23], off offset:16
	s_nop 0
	v_mov_b32_e32 v16, v120
	v_mov_b32_e32 v17, v121
	v_mov_b32_e32 v18, v122
	v_mov_b32_e32 v19, v123
	s_nop 0
	v_mov_b32_e32 v20, v136
	v_mov_b32_e32 v21, v137
	v_mov_b32_e32 v22, v138
	v_mov_b32_e32 v23, v139
	v_mov_b32_e32 v24, v140
	v_mov_b32_e32 v25, v141
	v_mov_b32_e32 v26, v142
	v_mov_b32_e32 v27, v143
	v_mov_b32_e32 v32, v124
	v_mov_b32_e32 v33, v125
	v_mov_b32_e32 v34, v126
	v_mov_b32_e32 v35, v127
	v_pk_mul_f32 v[36:37], v[2:3], v[42:43] op_sel_hi:[1,0]
	v_pk_fma_f32 v[0:1], v[20:21], v[0:1], v[16:17]
	v_pk_fma_f32 v[2:3], v[22:23], v[28:29], v[18:19]
	v_pk_fma_f32 v[16:17], v[24:25], v[36:37], v[32:33]
	v_pk_fma_f32 v[18:19], v[26:27], v[30:31], v[34:35]
	global_store_dwordx4 v[40:41], v[0:3], off offset:2048
	global_store_dwordx4 v[40:41], v[16:19], off offset:2064
	s_andn2_b64 exec, exec, s[0:1]
	s_cbranch_execnz .LBB0_1619
